# dn_prep X_bot on f32 matrix cores (v_mfma_f32_16x16x4_f32, f32 in/acc): 16 MFMA per wave instead of 256 VALU FMA + 64 LDS reads per thread
# speedup vs baseline: 1.0207x; 1.0081x over previous
; DI unsigned pk2(float lo, float hi) { f32x2_t v = {lo, hi}; bf16x2_t b = __builtin_convertvector(v, bf16x2_t); return __builtin_bit_cast(unsigned, b); }
; DI void dn_prep_item(const Params& p, int l, int item, int next_item, u32x4 (&pre)[12], unsigned char* lds, int tid) {
;     ...
;         {
;             const int c = tid & 127, rg = tid >> 7;
;             float xt[32];
; #pragma unroll
;             for (int k = 0; k < 32; ++k) xt[k] = XS[k * 129 + c];
; #pragma unroll
;             for (int ii = 0; ii < 8; ++ii) { const int i = rg * 8 + ii; float a0 = XS[(32 + i) * 129 + c], a1 = 0.f;
; #pragma unroll
;                 for (int k = 0; k < 32; k += 2) { a0 -= Zs[i * 33 + k] * xt[k]; a1 -= Zs[i * 33 + k + 1] * xt[k + 1]; }
;                 XS[(32 + i) * 129 + c] = a0 + a1; }
;         }
;     }
;     __syncthreads();
;     dn_prep_fetch(p, next_item < 2048 ? next_item : item, tid, pre);
;     {
;         const int chunk = (b * 8 + h) * 32 + n; unsigned char* base = p.ws + OFF_U + (size_t)chunk * PREP_CHUNK_BYTES;
;         const int f = tid >> 6, m = f >> 1, s = f & 1, r = lane & 15, g = lane >> 4, row = 16 * m + r, c0 = 32 * s + 4 * g, c1 = c0 + 16;
;         u32x4 w;
;         { const float* a = XS + row * 129 + 64; w.x = pk2(a[c0], a[c0 + 1]); w.y = pk2(a[c0 + 2], a[c0 + 3]); w.z = pk2(a[c1], a[c1 + 1]); w.w = pk2(a[c1 + 2], a[c1 + 3]); *(u32x4*)(base + (size_t)tid * 16) = w; }
; #pragma unroll
;         for (int q = 0; q < 2; ++q) { const int idx = tid * 2 + q, wm = idx >> 6, ln = idx & 63, vv = 16 * (wm >> 2) + (ln & 15), r0 = 16 * (wm & 3) + 4 * (ln >> 4);
;             u32x2 o; o.x = pk2(XS[r0 * 129 + vv], XS[(r0 + 1) * 129 + vv]); o.y = pk2(XS[(r0 + 2) * 129 + vv], XS[(r0 + 3) * 129 + vv]); *(u32x2*)(base + 32768 + (size_t)idx * 8) = o; }
;         if (tid == 0) ((float*)(p.ws + OFF_CD))[chunk] = EGs[63];
.LBB0_503:
	s_or_b64 exec, exec, s[8:9]
	v_ashrrev_i32_e32 v35, 4, v54
	v_and_b32_e32 v2, 0x7f, v54
	v_and_b32_e32 v38, -8, v35
	s_movk_i32 s12, 0x204
	v_lshl_add_u32 v36, v2, 2, v50
	v_mul_lo_u32 v40, v38, s12
	s_movk_i32 s5, 0x84
	v_add_u32_e32 v41, v36, v40
	v_mad_u64_u32 v[38:39], s[6:7], v38, s5, v[52:53]
	s_waitcnt lgkmcnt(0)
	s_barrier
	v_and_b32_e32 v2, 15, v206
	v_lshrrev_b32_e32 v3, 4, v206
	v_lshrrev_b32_e32 v4, 6, v54
	v_lshl_add_u32 v4, v4, 4, v2
	v_mul_u32_u24_e32 v5, 0x90, v2
	v_lshl_add_u32 v5, v3, 2, v5
	v_add_u32_e32 v5, v5, v52
	v_mul_u32_u24_e32 v6, 0x204, v3
	v_lshl_add_u32 v6, v4, 2, v6
	v_add_u32_e32 v6, v6, v50
	v_mul_u32_u24_e32 v7, 0x810, v3
	v_lshl_add_u32 v7, v4, 2, v7
	v_add_u32_e32 v7, v7, v50
	ds_read_b32 v8, v6
	ds_read_b32 v9, v6 offset:2064
	ds_read_b32 v10, v6 offset:4128
	ds_read_b32 v11, v6 offset:6192
	ds_read_b32 v12, v6 offset:8256
	ds_read_b32 v13, v6 offset:10320
	ds_read_b32 v14, v6 offset:12384
	ds_read_b32 v15, v6 offset:14448
	ds_read_b32 v16, v5
	ds_read_b32 v17, v5 offset:16
	ds_read_b32 v18, v5 offset:32
	ds_read_b32 v19, v5 offset:48
	ds_read_b32 v20, v5 offset:64
	ds_read_b32 v21, v5 offset:80
	ds_read_b32 v22, v5 offset:96
	ds_read_b32 v23, v5 offset:112
	ds_read_b32 v24, v5 offset:2304
	ds_read_b32 v25, v5 offset:2320
	ds_read_b32 v26, v5 offset:2336
	ds_read_b32 v27, v5 offset:2352
	ds_read_b32 v28, v5 offset:2368
	ds_read_b32 v29, v5 offset:2384
	ds_read_b32 v30, v5 offset:2400
	ds_read_b32 v31, v5 offset:2416
	ds_read_b32 v36, v7 offset:16512
	ds_read_b32 v37, v7 offset:17028
	ds_read_b32 v38, v7 offset:17544
	ds_read_b32 v39, v7 offset:18060
	ds_read_b32 v40, v7 offset:24768
	ds_read_b32 v41, v7 offset:25284
	ds_read_b32 v42, v7 offset:25800
	ds_read_b32 v43, v7 offset:26316
	s_waitcnt lgkmcnt(8)
	v_mfma_f32_16x16x4_f32 v[44:47], v16, v8, 0
	v_mfma_f32_16x16x4_f32 v[212:215], v24, v8, 0
	v_mfma_f32_16x16x4_f32 v[44:47], v17, v9, v[44:47]
	v_mfma_f32_16x16x4_f32 v[212:215], v25, v9, v[212:215]
	v_mfma_f32_16x16x4_f32 v[44:47], v18, v10, v[44:47]
	v_mfma_f32_16x16x4_f32 v[212:215], v26, v10, v[212:215]
	v_mfma_f32_16x16x4_f32 v[44:47], v19, v11, v[44:47]
	v_mfma_f32_16x16x4_f32 v[212:215], v27, v11, v[212:215]
	v_mfma_f32_16x16x4_f32 v[44:47], v20, v12, v[44:47]
	v_mfma_f32_16x16x4_f32 v[212:215], v28, v12, v[212:215]
	v_mfma_f32_16x16x4_f32 v[44:47], v21, v13, v[44:47]
	v_mfma_f32_16x16x4_f32 v[212:215], v29, v13, v[212:215]
	v_mfma_f32_16x16x4_f32 v[44:47], v22, v14, v[44:47]
	v_mfma_f32_16x16x4_f32 v[212:215], v30, v14, v[212:215]
	v_mfma_f32_16x16x4_f32 v[44:47], v23, v15, v[44:47]
	v_mfma_f32_16x16x4_f32 v[212:215], v31, v15, v[212:215]
	s_waitcnt lgkmcnt(0)
	s_nop 8
	v_sub_f32_e32 v36, v36, v44
	v_sub_f32_e32 v37, v37, v45
	v_sub_f32_e32 v38, v38, v46
	v_sub_f32_e32 v39, v39, v47
	v_sub_f32_e32 v40, v40, v212
	v_sub_f32_e32 v41, v41, v213
	v_sub_f32_e32 v42, v42, v214
	v_sub_f32_e32 v43, v43, v215
	ds_write_b32 v7, v36 offset:16512
	ds_write_b32 v7, v37 offset:17028
	ds_write_b32 v7, v38 offset:17544
	ds_write_b32 v7, v39 offset:18060
	ds_write_b32 v7, v40 offset:24768
	ds_write_b32 v7, v41 offset:25284
	ds_write_b32 v7, v42 offset:25800
	ds_write_b32 v7, v43 offset:26316
	s_add_i32 s4, s42, s33
	s_cmpk_gt_i32 s4, 0x7ff
	v_and_b32_e32 v66, -16, v77
	v_lshl_add_u64 v[62:63], s[26:27], 0, v[58:59]
	v_or_b32_e32 v58, v66, v61
	v_ashrrev_i32_e32 v57, 31, v56
	s_cselect_b64 s[6:7], -1, 0
	s_cmpk_lt_i32 s4, 0x800
	s_cselect_b32 s5, s4, s42
	s_lshl_b32 s8, s5, 3
	s_lshl_b32 s5, s5, 7
	s_and_b32 s10, s8, 0x7c0
	s_and_b32 s11, s8, 0xfffff800
	s_and_b32 s5, s5, 0x380
	s_add_u32 s8, s29, s5
	s_addc_u32 s9, s40, 0
	v_mov_b32_e32 v35, v165
	s_movk_i32 s5, 0xc00
	v_add_u32_e32 v10, s10, v77
	v_max_i32_e32 v10, 0, v10
	v_add_u32_e32 v10, s11, v10
	v_add3_u32 v8, s10, -3, v77
	v_max_i32_e32 v4, 0, v8
	v_max_i32_e32 v6, -1, v8
	v_max_i32_e32 v8, -2, v8
	v_lshl_add_u64 v[2:3], s[8:9], 0, v[34:35]
	v_add_u32_e32 v4, s11, v4
	v_add3_u32 v6, v6, s11, 1
	v_add3_u32 v8, v8, s11, 2
	v_mad_i64_i32 v[4:5], s[8:9], v4, s5, v[2:3]
	v_mad_i64_i32 v[6:7], s[8:9], v6, s5, v[2:3]
	v_mad_i64_i32 v[8:9], s[8:9], v8, s5, v[2:3]
	v_mad_i64_i32 v[2:3], s[8:9], v10, s5, v[2:3]
	s_waitcnt lgkmcnt(0)
	s_barrier
	global_load_dwordx4 v[46:49], v[4:5], off
	global_load_dwordx4 v[42:45], v[6:7], off
	global_load_dwordx4 v[38:41], v[8:9], off
	global_load_dwordx4 v[34:37], v[2:3], off
	global_load_dwordx4 v[30:33], v[4:5], off offset:1024
	global_load_dwordx4 v[26:29], v[6:7], off offset:1024
	global_load_dwordx4 v[22:25], v[8:9], off offset:1024
	global_load_dwordx4 v[18:21], v[2:3], off offset:1024
	global_load_dwordx4 v[14:17], v[4:5], off offset:2048
	global_load_dwordx4 v[10:13], v[6:7], off offset:2048
	s_nop 0
	global_load_dwordx4 v[6:9], v[8:9], off offset:2048
	s_nop 0
	global_load_dwordx4 v[2:5], v[2:3], off offset:2048
	v_mad_u64_u32 v[58:59], s[8:9], v58, s12, v[50:51]
	v_lshlrev_b32_e32 v59, 7, v60
	v_and_b32_e32 v59, 0x80, v59
	v_and_b32_e32 v60, 48, v54
	v_add3_u32 v64, v58, v59, v60
	ds_read2_b32 v[58:59], v64 offset0:64 offset1:65
	ds_read2_b32 v[60:61], v64 offset0:66 offset1:67
	s_waitcnt lgkmcnt(1)
	v_cvt_pk_bf16_f32 v58, v58, v59
	s_waitcnt lgkmcnt(0)
	v_cvt_pk_bf16_f32 v59, v60, v61
	ds_read2_b32 v[60:61], v64 offset0:80 offset1:81
	ds_read2_b32 v[64:65], v64 offset0:82 offset1:83
	s_waitcnt lgkmcnt(1)
	v_cvt_pk_bf16_f32 v60, v60, v61
	s_waitcnt lgkmcnt(0)
	v_cvt_pk_bf16_f32 v61, v64, v65
	v_lshl_add_u64 v[64:65], v[54:55], 4, v[62:63]
	v_lshrrev_b32_e32 v55, 1, v54
	global_store_dwordx4 v[64:65], v[58:61], off
	v_and_b32_e32 v55, 48, v55
	s_nop 0
	v_lshrrev_b32_e32 v58, 2, v56
	v_and_or_b32 v55, v58, 12, v55
	v_mul_u32_u24_e32 v55, 0x81, v55
	v_and_b32_e32 v58, 14, v56
	v_lshl_add_u32 v58, v58, 2, v50
	v_lshlrev_b32_e32 v59, 2, v66
	v_lshlrev_b32_e32 v55, 2, v55
	v_add3_u32 v55, v58, v59, v55
	ds_read2_b32 v[60:61], v55 offset1:1
	ds_read2_b32 v[64:65], v55 offset0:129 offset1:130
	v_add_u32_e32 v59, 0x408, v55
	v_add_u32_e32 v55, 0x60c, v55
	ds_read2_b32 v[66:67], v59 offset1:1
	ds_read2_b32 v[78:79], v55 offset1:1
	v_lshl_add_u64 v[56:57], v[56:57], 3, v[62:63]
	v_add_co_u32_e32 v56, vcc, 0x8000, v56
	s_waitcnt lgkmcnt(2)
	v_cvt_pk_bf16_f32 v58, v60, v64
	v_addc_co_u32_e32 v57, vcc, 0, v57, vcc
	s_waitcnt lgkmcnt(0)
	v_cvt_pk_bf16_f32 v59, v66, v78
	v_cvt_pk_bf16_f32 v60, v61, v65
	v_cvt_pk_bf16_f32 v61, v67, v79
	v_cmp_eq_u32_e32 vcc, 0, v54
	global_store_dwordx4 v[56:57], v[58:61], off
	s_and_saveexec_b64 s[8:9], vcc
	s_cbranch_execz .LBB0_280
	ds_read_b32 v54, v76
	v_lshl_add_u64 v[0:1], v[0:1], 2, s[38:39]
	s_waitcnt lgkmcnt(0)
	global_store_dword v[0:1], v54, off
	s_branch .LBB0_280
